# GLA group-B dec fragments filled by one LDS-DMA piece (512 distinct bytes) and read with broadcast addresses: 17 instead of 32 pieces per chunk
# baseline (speedup 1.0000x reference)
; #define LAS __attribute__((address_space(3)))
; #define DMA16(gptr, lptr) __builtin_amdgcn_global_load_lds((const unsigned*)(gptr), (LAS unsigned*)(lptr), 16, 0, 0)
; __device__ __forceinline__ void gla_issue_B(const P& p, int ch, LAS unsigned char* bufB, int r, int hh) {
; #pragma unroll
;     for (int d = 0; d < 4; ++d)
; #pragma unroll
;         for (int ks = 0; ks < 4; ++ks) DMA16(p.GKT + ((size_t)ch * 128 + 32 * d + r) * 64 + 16 * ks + 8 * hh, bufB + (d * 4 + ks) * 1024);
; #pragma unroll
;     for (int d = 0; d < 4; ++d)
; #pragma unroll
;         for (int g = 0; g < 4; ++g) DMA16(p.GDEC + (size_t)ch * 128 + 32 * d + 8 * g + 4 * hh, bufB + (16 + d * 4 + g) * 1024);
; }
.LBB0_1463:
	s_andn2_b64 vcc, exec, s[12:13]
	s_mov_b32 s9, s44
	s_cbranch_vccnz .LBB0_1465
	s_ashr_i32 s9, s8, 31
	s_lshl_b64 s[12:13], s[8:9], 14
	v_lshl_add_u64 v[6:7], v[158:159], 0, s[12:13]
	v_lshl_add_u64 v[6:7], v[6:7], 0, v[162:163]
	s_add_i32 m0, s34, 0x4000
	v_lshl_add_u64 v[8:9], v[6:7], 0, 32
	global_load_lds_dwordx4 v[6:7], off
	s_mov_b32 m0, s47
	s_mov_b64 s[14:15], 0x60
	global_load_lds_dwordx4 v[8:9], off
	v_lshl_add_u64 v[8:9], v[6:7], 0, 64
	s_mov_b32 m0, s48
	s_mov_b64 s[12:13], 0x1000
	global_load_lds_dwordx4 v[8:9], off
	v_lshl_add_u64 v[8:9], v[6:7], 0, s[14:15]
	s_mov_b32 m0, s49
	s_nop 0
	global_load_lds_dwordx4 v[8:9], off
	v_lshl_add_u64 v[8:9], v[6:7], 0, s[12:13]
	s_add_i32 m0, s34, 0x5000
	s_mov_b64 s[12:13], 0x1020
	global_load_lds_dwordx4 v[8:9], off
	v_lshl_add_u64 v[8:9], v[6:7], 0, s[12:13]
	s_mov_b32 m0, s55
	s_mov_b64 s[12:13], 0x1040
	global_load_lds_dwordx4 v[8:9], off
	v_lshl_add_u64 v[8:9], v[6:7], 0, s[12:13]
	s_mov_b32 m0, s56
	s_mov_b64 s[12:13], 0x1060
	global_load_lds_dwordx4 v[8:9], off
	v_lshl_add_u64 v[8:9], v[6:7], 0, s[12:13]
	s_mov_b32 m0, s57
	s_mov_b64 s[12:13], 0x2000
	global_load_lds_dwordx4 v[8:9], off
	v_lshl_add_u64 v[8:9], v[6:7], 0, s[12:13]
	s_add_i32 m0, s34, 0x6000
	s_mov_b64 s[12:13], 0x2020
	global_load_lds_dwordx4 v[8:9], off
	v_lshl_add_u64 v[8:9], v[6:7], 0, s[12:13]
	s_mov_b32 m0, s92
	s_mov_b64 s[12:13], 0x2040
	global_load_lds_dwordx4 v[8:9], off
	v_lshl_add_u64 v[8:9], v[6:7], 0, s[12:13]
	s_mov_b32 m0, s93
	s_mov_b64 s[12:13], 0x2060
	global_load_lds_dwordx4 v[8:9], off
	v_lshl_add_u64 v[8:9], v[6:7], 0, s[12:13]
	s_mov_b32 m0, s96
	s_mov_b64 s[12:13], 0x3000
	global_load_lds_dwordx4 v[8:9], off
	v_lshl_add_u64 v[8:9], v[6:7], 0, s[12:13]
	s_add_i32 m0, s34, 0x7000
	s_mov_b64 s[12:13], 0x3020
	global_load_lds_dwordx4 v[8:9], off
	v_lshl_add_u64 v[8:9], v[6:7], 0, s[12:13]
	s_mov_b32 m0, s97
	s_mov_b64 s[12:13], 0x3040
	global_load_lds_dwordx4 v[8:9], off
	v_lshl_add_u64 v[8:9], v[6:7], 0, s[12:13]
	s_mov_b32 m0, s54
	s_mov_b64 s[12:13], 0x3060
	global_load_lds_dwordx4 v[8:9], off
	v_lshl_add_u64 v[6:7], v[6:7], 0, s[12:13]
	s_mov_b32 m0, s16
	s_lshl_b64 s[12:13], s[8:9], 9
	global_load_lds_dwordx4 v[6:7], off
	v_mbcnt_lo_u32_b32 v8, -1, 0
	v_mbcnt_hi_u32_b32 v8, -1, v8
	v_lshrrev_b32_e32 v9, 5, v8
	v_lshlrev_b32_e32 v8, 4, v8
	v_mul_u32_u24_e32 v9, 0x210, v9
	v_sub_u32_e32 v8, v8, v9
	v_ashrrev_i32_e32 v9, 31, v8
	v_lshl_add_u64 v[6:7], v[160:161], 0, v[8:9]
	v_lshl_add_u64 v[6:7], v[6:7], 0, s[12:13]
	s_add_i32 s9, s34, 0x8000

; __device__ __forceinline__ f32x16 mma32(bf16x8 a, bf16x8 b, f32x16 c) { return __builtin_amdgcn_mfma_f32_32x32x16_bf16(a, b, c, 0, 0, 0); }
; #define LDS_WAIT() asm volatile("s_waitcnt lgkmcnt(0)" ::: "memory")
; __device__ __forceinline__ void gla_scan_task(const P& p, int l, int s, int h, int sl, LAS unsigned char* ldsw, int lane) {
;     ...
; #pragma unroll
;         for (int d = 0; d < 4; ++d) {
; #pragma unroll
;             for (int ks = 0; ks < 4; ++ks) S[d] = mma32(FRAG16(bufB, d * 4 + ks, lane), vb[ks], S[d]);
; #pragma unroll
;             for (int g = 0; g < 4; ++g) { const f32x4v dc = FRAGF4(bufB, 16 + d * 4 + g, lane); S[d][4 * g] *= dc.x; S[d][4 * g + 1] *= dc.y; S[d][4 * g + 2] *= dc.z; S[d][4 * g + 3] *= dc.w; }
;         }
;         LDS_WAIT();
;         if (SCAN_LOADERS) { if (lane == 0) FL[4] = (unsigned)n + 1u; } else gla_issue_B(p, chn, bufB, r, hh);
.LBB0_1556:
	s_waitcnt lgkmcnt(0)
	v_lshrrev_b32_e32 v173, 5, v209
	v_and_b32_e32 v173, 16, v173
	v_add_u32_e32 v173, 0xf000, v173
	ds_read_b128 v[236:239], v209 offset:45056
	ds_read_b128 v[240:243], v209 offset:46080
	ds_read_b128 v[244:247], v209 offset:47104
	ds_read_b128 v[168:171], v209 offset:48128
	ds_read_b128 v[212:215], v209 offset:49152
	ds_read_b128 v[216:219], v209 offset:50176
	s_waitcnt lgkmcnt(5)
	v_mfma_f32_32x32x16_bf16 v[50:65], v[236:239], v[94:97], v[50:65]
	ds_read_b128 v[220:223], v209 offset:51200
	s_waitcnt lgkmcnt(5)
	v_mfma_f32_32x32x16_bf16 v[50:65], v[240:243], v[90:93], v[50:65]
	ds_read_b128 v[224:227], v209 offset:52224
	s_waitcnt lgkmcnt(5)
	v_mfma_f32_32x32x16_bf16 v[50:65], v[244:247], v[86:89], v[50:65]
	ds_read_b128 v[228:231], v209 offset:53248
	s_waitcnt lgkmcnt(5)
	v_mfma_f32_32x32x16_bf16 v[50:65], v[168:171], v[82:85], v[50:65]
	ds_read_b128 v[98:101], v173
	ds_read_b128 v[74:77], v173 offset:32
	ds_read_b128 v[70:73], v173 offset:64
	ds_read_b128 v[66:69], v173 offset:96
	ds_read_b128 v[232:235], v209 offset:54272
	s_waitcnt lgkmcnt(9)
	v_mfma_f32_32x32x16_bf16 v[34:49], v[212:215], v[94:97], v[34:49]
	ds_read_b128 v[236:239], v209 offset:55296
	s_waitcnt lgkmcnt(9)
	v_mfma_f32_32x32x16_bf16 v[34:49], v[216:219], v[90:93], v[34:49]
	ds_read_b128 v[240:243], v209 offset:56320
	s_waitcnt lgkmcnt(9)
	v_mfma_f32_32x32x16_bf16 v[34:49], v[220:223], v[86:89], v[34:49]
	ds_read_b128 v[244:247], v209 offset:57344
	s_waitcnt lgkmcnt(9)
	v_mfma_f32_32x32x16_bf16 v[34:49], v[224:227], v[82:85], v[34:49]
	ds_read_b128 v[110:113], v173 offset:128
	ds_read_b128 v[106:109], v173 offset:160
	ds_read_b128 v[102:105], v173 offset:192
	ds_read_b128 v[78:81], v173 offset:224
	ds_read_b128 v[168:171], v209 offset:58368
	s_waitcnt lgkmcnt(13)
	v_mfma_f32_32x32x16_bf16 v[18:33], v[228:231], v[94:97], v[18:33]
	ds_read_b128 v[212:215], v209 offset:59392
	s_waitcnt lgkmcnt(9)
	v_mfma_f32_32x32x16_bf16 v[18:33], v[232:235], v[90:93], v[18:33]
	ds_read_b128 v[216:219], v209 offset:60416
	s_waitcnt lgkmcnt(9)
	v_mfma_f32_32x32x16_bf16 v[18:33], v[236:239], v[86:89], v[18:33]
	s_waitcnt lgkmcnt(8)
	v_mfma_f32_32x32x16_bf16 v[18:33], v[240:243], v[82:85], v[18:33]
	ds_read_b128 v[126:129], v173 offset:256
	ds_read_b128 v[122:125], v173 offset:288
	ds_read_b128 v[118:121], v173 offset:320
	ds_read_b128 v[114:117], v173 offset:352
	s_waitcnt lgkmcnt(11)
	v_mfma_f32_32x32x16_bf16 v[2:17], v[244:247], v[94:97], v[2:17]
	s_waitcnt lgkmcnt(6)
	v_mfma_f32_32x32x16_bf16 v[2:17], v[168:171], v[90:93], v[2:17]
	s_waitcnt lgkmcnt(5)
	v_mfma_f32_32x32x16_bf16 v[2:17], v[212:215], v[86:89], v[2:17]
	s_waitcnt lgkmcnt(4)
	v_mfma_f32_32x32x16_bf16 v[2:17], v[216:219], v[82:85], v[2:17]
	ds_read_b128 v[90:93], v173 offset:384
	ds_read_b128 v[94:97], v173 offset:416
	ds_read_b128 v[82:85], v173 offset:448
	ds_read_b128 v[86:89], v173 offset:480
	s_waitcnt lgkmcnt(0)
	s_and_saveexec_b64 s[8:9], s[0:1]
	s_cbranch_execz .LBB0_1520
	v_mov_b32_e32 v132, s7
	ds_write_b32 v163, v132 offset:13328
	s_branch .LBB0_1520
